# v133 plus software-pipelined leader polling of the arrival counter (two polls in flight)
# baseline (speedup 1.0000x reference)
.LBB0_668:
	s_or_b64 exec, exec, s[8:9]
	buffer_inv sc1
	s_waitcnt vmcnt(0)
	v_readfirstlane_b32 s6, v2
	v_cvt_f32_u32_e32 v2, v0
	v_sub_u32_e32 v3, 0, v0
	v_add_u32_e32 v1, s6, v1
	v_readlane_b32 s6, v245, 13
	v_rcp_iflag_f32_e32 v2, v2
	v_readlane_b32 s7, v245, 14
	s_mov_b64 s[8:9], -1
	v_mul_f32_e32 v2, 0x4f7ffffe, v2
	v_cvt_u32_f32_e32 v2, v2
	v_mul_lo_u32 v3, v3, v2
	v_mul_hi_u32 v3, v2, v3
	v_add_u32_e32 v2, v2, v3
	v_mul_hi_u32 v2, v1, v2
	v_mul_lo_u32 v3, v2, v0
	v_sub_u32_e32 v3, v1, v3
	v_cmp_ge_u32_e32 vcc, v3, v0
	v_add_u32_e32 v4, 1, v2
	v_add_u32_e32 v1, 1, v1
	v_cndmask_b32_e32 v2, v2, v4, vcc
	v_sub_u32_e32 v4, v3, v0
	v_cndmask_b32_e32 v3, v3, v4, vcc
	v_cmp_ge_u32_e32 vcc, v3, v0
	v_add_u32_e32 v3, 1, v2
	s_nop 0
	v_cndmask_b32_e32 v2, v2, v3, vcc
	v_mul_lo_u32 v3, v0, v2
	v_add_u32_e32 v0, v3, v0
	v_cmp_ne_u32_e32 vcc, v1, v0
	v_mov_b32_e32 v4, v0
	v_mov_b64_e32 v[0:1], s[6:7]
	s_and_saveexec_b64 s[6:7], vcc
	s_cbranch_execz .LBB0_680
	v_readlane_b32 s8, v245, 11
	v_readlane_b32 s9, v245, 12
	s_mov_b64 s[10:11], 0
	s_mov_b32 s20, 0
	s_nop 4
	global_load_dword v0, v137, s[8:9] sc1
